# attention prompt unit P.V loop: V fragments read from LDS through an 8-deep register ring with counted lgkmcnt waits instead of read-wait-MFMA on one register quad
# speedup vs baseline: 1.0103x; 1.0046x over previous
.LBB0_498:
	s_mul_i32 s0, s4, 0x10800
	v_add_u32_e32 v140, s0, v131
	v_add_u32_e32 v141, 0x4000, v140
	v_add_u32_e32 v142, 0x8000, v140
	v_add_u32_e32 v143, 0xc000, v140
	s_lshl_b32 s30, s4, 8
	s_mov_b32 s4, 1
	s_and_b64 vcc, exec, s[2:3]
	s_mov_b64 s[2:3], 0
	ds_read2_b64 v[132:135], v140 offset1:2
	ds_read2_b64 v[136:139], v141 offset0:64 offset1:66
	ds_read2_b64 v[144:147], v142 offset0:128 offset1:130
	ds_read2_b64 v[148:151], v143 offset0:192 offset1:194
	ds_read2_b64 v[152:155], v140 offset0:4 offset1:6
	ds_read2_b64 v[158:161], v141 offset0:68 offset1:70
	ds_read2_b64 v[162:165], v142 offset0:132 offset1:134
	ds_read2_b64 v[166:169], v143 offset0:196 offset1:198
	s_waitcnt lgkmcnt(7)
	v_mfma_f32_32x32x16_bf16 v[48:63], v[132:135], v[112:115], 0
	ds_read2_b64 v[132:135], v140 offset0:8 offset1:10
	s_waitcnt lgkmcnt(7)
	v_mfma_f32_32x32x16_bf16 v[32:47], v[136:139], v[112:115], 0
	ds_read2_b64 v[136:139], v141 offset0:72 offset1:74
	s_waitcnt lgkmcnt(7)
	v_mfma_f32_32x32x16_bf16 v[16:31], v[144:147], v[112:115], 0
	ds_read2_b64 v[144:147], v142 offset0:136 offset1:138
	s_waitcnt lgkmcnt(7)
	v_mfma_f32_32x32x16_bf16 v[0:15], v[148:151], v[112:115], 0
	ds_read2_b64 v[148:151], v143 offset0:200 offset1:202
	s_waitcnt lgkmcnt(7)
	v_mfma_f32_32x32x16_bf16 v[48:63], v[152:155], v[116:119], v[48:63]
	ds_read2_b64 v[152:155], v140 offset0:12 offset1:14
	s_waitcnt lgkmcnt(7)
	v_mfma_f32_32x32x16_bf16 v[32:47], v[158:161], v[116:119], v[32:47]
	ds_read2_b64 v[158:161], v141 offset0:76 offset1:78
	s_waitcnt lgkmcnt(7)
	v_mfma_f32_32x32x16_bf16 v[16:31], v[162:165], v[116:119], v[16:31]
	ds_read2_b64 v[162:165], v142 offset0:140 offset1:142
	s_waitcnt lgkmcnt(7)
	v_mfma_f32_32x32x16_bf16 v[0:15], v[166:169], v[116:119], v[0:15]
	ds_read2_b64 v[166:169], v143 offset0:204 offset1:206
	s_waitcnt lgkmcnt(7)
	v_mfma_f32_32x32x16_bf16 v[48:63], v[132:135], v[96:99], v[48:63]
	ds_read2_b64 v[132:135], v140 offset0:16 offset1:18
	s_waitcnt lgkmcnt(7)
	v_mfma_f32_32x32x16_bf16 v[32:47], v[136:139], v[96:99], v[32:47]
	ds_read2_b64 v[136:139], v141 offset0:80 offset1:82
	s_waitcnt lgkmcnt(7)
	v_mfma_f32_32x32x16_bf16 v[16:31], v[144:147], v[96:99], v[16:31]
	ds_read2_b64 v[144:147], v142 offset0:144 offset1:146
	s_waitcnt lgkmcnt(7)
	v_mfma_f32_32x32x16_bf16 v[0:15], v[148:151], v[96:99], v[0:15]
	ds_read2_b64 v[148:151], v143 offset0:208 offset1:210
	s_waitcnt lgkmcnt(7)
	v_mfma_f32_32x32x16_bf16 v[48:63], v[152:155], v[100:103], v[48:63]
	ds_read2_b64 v[152:155], v140 offset0:20 offset1:22
	s_waitcnt lgkmcnt(7)
	v_mfma_f32_32x32x16_bf16 v[32:47], v[158:161], v[100:103], v[32:47]
	ds_read2_b64 v[158:161], v141 offset0:84 offset1:86
	s_waitcnt lgkmcnt(7)
	v_mfma_f32_32x32x16_bf16 v[16:31], v[162:165], v[100:103], v[16:31]
	ds_read2_b64 v[162:165], v142 offset0:148 offset1:150
	s_waitcnt lgkmcnt(7)
	v_mfma_f32_32x32x16_bf16 v[0:15], v[166:169], v[100:103], v[0:15]
	ds_read2_b64 v[166:169], v143 offset0:212 offset1:214
	s_waitcnt lgkmcnt(7)
	v_mfma_f32_32x32x16_bf16 v[48:63], v[132:135], v[80:83], v[48:63]
	ds_read2_b64 v[132:135], v140 offset0:24 offset1:26
	s_waitcnt lgkmcnt(7)
	v_mfma_f32_32x32x16_bf16 v[32:47], v[136:139], v[80:83], v[32:47]
	ds_read2_b64 v[136:139], v141 offset0:88 offset1:90
	s_waitcnt lgkmcnt(7)
	v_mfma_f32_32x32x16_bf16 v[16:31], v[144:147], v[80:83], v[16:31]
	ds_read2_b64 v[144:147], v142 offset0:152 offset1:154
	s_waitcnt lgkmcnt(7)
	v_mfma_f32_32x32x16_bf16 v[0:15], v[148:151], v[80:83], v[0:15]
	ds_read2_b64 v[148:151], v143 offset0:216 offset1:218
	s_waitcnt lgkmcnt(7)
	v_mfma_f32_32x32x16_bf16 v[48:63], v[152:155], v[84:87], v[48:63]
	ds_read2_b64 v[152:155], v140 offset0:28 offset1:30
	s_waitcnt lgkmcnt(7)
	v_mfma_f32_32x32x16_bf16 v[32:47], v[158:161], v[84:87], v[32:47]
	ds_read2_b64 v[158:161], v141 offset0:92 offset1:94
	s_waitcnt lgkmcnt(7)
	v_mfma_f32_32x32x16_bf16 v[16:31], v[162:165], v[84:87], v[16:31]
	ds_read2_b64 v[162:165], v142 offset0:156 offset1:158
	s_waitcnt lgkmcnt(7)
	v_mfma_f32_32x32x16_bf16 v[0:15], v[166:169], v[84:87], v[0:15]
	ds_read2_b64 v[166:169], v143 offset0:220 offset1:222
	s_waitcnt lgkmcnt(7)
	v_mfma_f32_32x32x16_bf16 v[48:63], v[132:135], v[64:67], v[48:63]
	ds_read2_b64 v[132:135], v140 offset0:32 offset1:34
	s_waitcnt lgkmcnt(7)
	v_mfma_f32_32x32x16_bf16 v[32:47], v[136:139], v[64:67], v[32:47]
	ds_read2_b64 v[136:139], v141 offset0:96 offset1:98
	s_waitcnt lgkmcnt(7)
	v_mfma_f32_32x32x16_bf16 v[16:31], v[144:147], v[64:67], v[16:31]
	ds_read2_b64 v[144:147], v142 offset0:160 offset1:162
	s_waitcnt lgkmcnt(7)
	v_mfma_f32_32x32x16_bf16 v[0:15], v[148:151], v[64:67], v[0:15]
	ds_read2_b64 v[148:151], v143 offset0:224 offset1:226
	s_waitcnt lgkmcnt(7)
	v_mfma_f32_32x32x16_bf16 v[48:63], v[152:155], v[68:71], v[48:63]
	ds_read2_b64 v[152:155], v140 offset0:36 offset1:38
	s_waitcnt lgkmcnt(7)
	v_mfma_f32_32x32x16_bf16 v[32:47], v[158:161], v[68:71], v[32:47]
	ds_read2_b64 v[158:161], v141 offset0:100 offset1:102
	s_waitcnt lgkmcnt(7)
	v_mfma_f32_32x32x16_bf16 v[16:31], v[162:165], v[68:71], v[16:31]
	ds_read2_b64 v[162:165], v142 offset0:164 offset1:166
	s_waitcnt lgkmcnt(7)
	v_mfma_f32_32x32x16_bf16 v[0:15], v[166:169], v[68:71], v[0:15]
	ds_read2_b64 v[166:169], v143 offset0:228 offset1:230
	s_waitcnt lgkmcnt(7)
	v_mfma_f32_32x32x16_bf16 v[48:63], v[132:135], v[72:75], v[48:63]
	ds_read2_b64 v[132:135], v140 offset0:40 offset1:42
	s_waitcnt lgkmcnt(7)
	v_mfma_f32_32x32x16_bf16 v[32:47], v[136:139], v[72:75], v[32:47]
	ds_read2_b64 v[136:139], v141 offset0:104 offset1:106
	s_waitcnt lgkmcnt(7)
	v_mfma_f32_32x32x16_bf16 v[16:31], v[144:147], v[72:75], v[16:31]
	ds_read2_b64 v[144:147], v142 offset0:168 offset1:170
	s_waitcnt lgkmcnt(7)
	v_mfma_f32_32x32x16_bf16 v[0:15], v[148:151], v[72:75], v[0:15]
	ds_read2_b64 v[148:151], v143 offset0:232 offset1:234
	s_waitcnt lgkmcnt(7)
	v_mfma_f32_32x32x16_bf16 v[48:63], v[152:155], v[76:79], v[48:63]
	ds_read2_b64 v[152:155], v140 offset0:44 offset1:46
	s_waitcnt lgkmcnt(7)
	v_mfma_f32_32x32x16_bf16 v[32:47], v[158:161], v[76:79], v[32:47]
	ds_read2_b64 v[158:161], v141 offset0:108 offset1:110
	s_waitcnt lgkmcnt(7)
	v_mfma_f32_32x32x16_bf16 v[16:31], v[162:165], v[76:79], v[16:31]
	ds_read2_b64 v[162:165], v142 offset0:172 offset1:174
	s_waitcnt lgkmcnt(7)
	v_mfma_f32_32x32x16_bf16 v[0:15], v[166:169], v[76:79], v[0:15]
	ds_read2_b64 v[166:169], v143 offset0:236 offset1:238
	s_waitcnt lgkmcnt(7)
	v_mfma_f32_32x32x16_bf16 v[48:63], v[132:135], v[88:91], v[48:63]
	ds_read2_b64 v[132:135], v140 offset0:48 offset1:50
	s_waitcnt lgkmcnt(7)
	v_mfma_f32_32x32x16_bf16 v[32:47], v[136:139], v[88:91], v[32:47]
	ds_read2_b64 v[136:139], v141 offset0:112 offset1:114
	s_waitcnt lgkmcnt(7)
	v_mfma_f32_32x32x16_bf16 v[16:31], v[144:147], v[88:91], v[16:31]
	ds_read2_b64 v[144:147], v142 offset0:176 offset1:178
	s_waitcnt lgkmcnt(7)
	v_mfma_f32_32x32x16_bf16 v[0:15], v[148:151], v[88:91], v[0:15]
	ds_read2_b64 v[148:151], v143 offset0:240 offset1:242
	s_waitcnt lgkmcnt(7)
	v_mfma_f32_32x32x16_bf16 v[48:63], v[152:155], v[92:95], v[48:63]
	ds_read2_b64 v[152:155], v140 offset0:52 offset1:54
	s_waitcnt lgkmcnt(7)
	v_mfma_f32_32x32x16_bf16 v[32:47], v[158:161], v[92:95], v[32:47]
	ds_read2_b64 v[158:161], v141 offset0:116 offset1:118
	s_waitcnt lgkmcnt(7)
	v_mfma_f32_32x32x16_bf16 v[16:31], v[162:165], v[92:95], v[16:31]
	ds_read2_b64 v[162:165], v142 offset0:180 offset1:182
	s_waitcnt lgkmcnt(7)
	v_mfma_f32_32x32x16_bf16 v[0:15], v[166:169], v[92:95], v[0:15]
	ds_read2_b64 v[166:169], v143 offset0:244 offset1:246
	s_waitcnt lgkmcnt(7)
	v_mfma_f32_32x32x16_bf16 v[48:63], v[132:135], v[104:107], v[48:63]
	ds_read2_b64 v[132:135], v140 offset0:56 offset1:58
	s_waitcnt lgkmcnt(7)
	v_mfma_f32_32x32x16_bf16 v[32:47], v[136:139], v[104:107], v[32:47]
	ds_read2_b64 v[136:139], v141 offset0:120 offset1:122
	s_waitcnt lgkmcnt(7)
	v_mfma_f32_32x32x16_bf16 v[16:31], v[144:147], v[104:107], v[16:31]
	ds_read2_b64 v[144:147], v142 offset0:184 offset1:186
	s_waitcnt lgkmcnt(7)
	v_mfma_f32_32x32x16_bf16 v[0:15], v[148:151], v[104:107], v[0:15]
	ds_read2_b64 v[148:151], v143 offset0:248 offset1:250
	s_waitcnt lgkmcnt(7)
	v_mfma_f32_32x32x16_bf16 v[48:63], v[152:155], v[108:111], v[48:63]
	ds_read2_b64 v[152:155], v140 offset0:60 offset1:62
	s_waitcnt lgkmcnt(7)
	v_mfma_f32_32x32x16_bf16 v[32:47], v[158:161], v[108:111], v[32:47]
	ds_read2_b64 v[158:161], v141 offset0:124 offset1:126
	s_waitcnt lgkmcnt(7)
	v_mfma_f32_32x32x16_bf16 v[16:31], v[162:165], v[108:111], v[16:31]
	ds_read2_b64 v[162:165], v142 offset0:188 offset1:190
	s_waitcnt lgkmcnt(7)
	v_mfma_f32_32x32x16_bf16 v[0:15], v[166:169], v[108:111], v[0:15]
	ds_read2_b64 v[166:169], v143 offset0:252 offset1:254
	s_waitcnt lgkmcnt(7)
	v_mfma_f32_32x32x16_bf16 v[48:63], v[132:135], v[120:123], v[48:63]
	s_waitcnt lgkmcnt(6)
	v_mfma_f32_32x32x16_bf16 v[32:47], v[136:139], v[120:123], v[32:47]
	s_waitcnt lgkmcnt(5)
	v_mfma_f32_32x32x16_bf16 v[16:31], v[144:147], v[120:123], v[16:31]
	s_waitcnt lgkmcnt(4)
	v_mfma_f32_32x32x16_bf16 v[0:15], v[148:151], v[120:123], v[0:15]
	s_waitcnt lgkmcnt(3)
	v_mfma_f32_32x32x16_bf16 v[48:63], v[152:155], v[124:127], v[48:63]
	s_waitcnt lgkmcnt(2)
	v_mfma_f32_32x32x16_bf16 v[32:47], v[158:161], v[124:127], v[32:47]
	s_waitcnt lgkmcnt(1)
	v_mfma_f32_32x32x16_bf16 v[16:31], v[162:165], v[124:127], v[16:31]
	s_waitcnt lgkmcnt(0)
	v_mfma_f32_32x32x16_bf16 v[0:15], v[166:169], v[124:127], v[0:15]
	s_nop 9
	v_mul_f32_e32 v32, v130, v32
	v_mul_f32_e32 v33, v130, v33
	v_mul_f32_e32 v48, v130, v48
	v_mul_f32_e32 v49, v130, v49
	v_cvt_pk_bf16_f32 v48, v48, v49
	v_mul_f32_e32 v49, v130, v50
	v_mul_f32_e32 v50, v130, v51
	v_cvt_pk_bf16_f32 v49, v49, v50
	v_mul_f32_e32 v50, v130, v52
	v_mul_f32_e32 v51, v130, v53
	v_cvt_pk_bf16_f32 v50, v50, v51
	v_mul_f32_e32 v51, v130, v54
	v_mul_f32_e32 v52, v130, v55
	v_cvt_pk_bf16_f32 v51, v51, v52
	s_nop 1
	v_lshl_add_u64 v[132:133], v[128:129], 0, s[30:31]
	v_permlane32_swap_b32_e32 v48, v50
	v_permlane32_swap_b32_e32 v49, v51
	global_store_dwordx4 v[132:133], v[48:51], off
	v_mul_f32_e32 v52, v130, v63
	v_mul_f32_e32 v16, v130, v16
	v_mul_f32_e32 v48, v130, v56
	v_mul_f32_e32 v49, v130, v57
	v_cvt_pk_bf16_f32 v48, v48, v49
	v_mul_f32_e32 v49, v130, v58
	v_mul_f32_e32 v50, v130, v59
	v_cvt_pk_bf16_f32 v49, v49, v50
	v_mul_f32_e32 v50, v130, v60
	v_mul_f32_e32 v51, v130, v61
	v_cvt_pk_bf16_f32 v50, v50, v51
	v_mul_f32_e32 v51, v130, v62
	v_cvt_pk_bf16_f32 v51, v51, v52
	v_mul_f32_e32 v17, v130, v17
	s_nop 1
	v_mul_f32_e32 v0, v130, v0
	v_permlane32_swap_b32_e32 v48, v50
	v_permlane32_swap_b32_e32 v49, v51
	global_store_dwordx4 v[132:133], v[48:51], off offset:32
	v_cvt_pk_bf16_f32 v32, v32, v33
	v_mul_f32_e32 v33, v130, v34
	v_mul_f32_e32 v34, v130, v35
	v_cvt_pk_bf16_f32 v33, v33, v34
	v_mul_f32_e32 v34, v130, v36
	v_mul_f32_e32 v35, v130, v37
	v_cvt_pk_bf16_f32 v34, v34, v35
	v_mul_f32_e32 v35, v130, v38
	v_mul_f32_e32 v36, v130, v39
	v_cvt_pk_bf16_f32 v35, v35, v36
	v_mul_f32_e32 v36, v130, v47
	s_nop 1
	v_mul_f32_e32 v1, v130, v1
	v_permlane32_swap_b32_e32 v32, v34
	v_permlane32_swap_b32_e32 v33, v35
	global_store_dwordx4 v[132:133], v[32:35], off offset:64
	s_nop 1
	v_mul_f32_e32 v32, v130, v40
	v_mul_f32_e32 v33, v130, v41
	v_cvt_pk_bf16_f32 v32, v32, v33
	v_mul_f32_e32 v33, v130, v42
	v_mul_f32_e32 v34, v130, v43
	v_cvt_pk_bf16_f32 v33, v33, v34
	v_mul_f32_e32 v34, v130, v44
	v_mul_f32_e32 v35, v130, v45
	v_cvt_pk_bf16_f32 v34, v34, v35
	v_mul_f32_e32 v35, v130, v46
	v_cvt_pk_bf16_f32 v35, v35, v36
	s_nop 0
	s_nop 1
	s_nop 0
	v_permlane32_swap_b32_e32 v32, v34
	v_permlane32_swap_b32_e32 v33, v35
	global_store_dwordx4 v[132:133], v[32:35], off offset:96
	v_cvt_pk_bf16_f32 v16, v16, v17
	v_mul_f32_e32 v17, v130, v18
	v_mul_f32_e32 v18, v130, v19
	v_cvt_pk_bf16_f32 v17, v17, v18
	v_mul_f32_e32 v18, v130, v20
	v_mul_f32_e32 v19, v130, v21
	v_cvt_pk_bf16_f32 v18, v18, v19
	v_mul_f32_e32 v19, v130, v22
	v_mul_f32_e32 v20, v130, v23
	v_cvt_pk_bf16_f32 v19, v19, v20
	v_mul_f32_e32 v20, v130, v31
	s_nop 1
	s_nop 0
	v_permlane32_swap_b32_e32 v16, v18
	v_permlane32_swap_b32_e32 v17, v19
	global_store_dwordx4 v[132:133], v[16:19], off offset:128
	s_nop 1
	v_mul_f32_e32 v16, v130, v24
	v_mul_f32_e32 v17, v130, v25
	v_cvt_pk_bf16_f32 v16, v16, v17
	v_mul_f32_e32 v17, v130, v26
	v_mul_f32_e32 v18, v130, v27
	v_cvt_pk_bf16_f32 v17, v17, v18
	v_mul_f32_e32 v18, v130, v28
	v_mul_f32_e32 v19, v130, v29
	v_cvt_pk_bf16_f32 v18, v18, v19
	v_mul_f32_e32 v19, v130, v30
	v_cvt_pk_bf16_f32 v19, v19, v20
	s_nop 0
	s_nop 1
	s_nop 0
	v_permlane32_swap_b32_e32 v16, v18
	v_permlane32_swap_b32_e32 v17, v19
	global_store_dwordx4 v[132:133], v[16:19], off offset:160
	v_cvt_pk_bf16_f32 v0, v0, v1
	v_mul_f32_e32 v1, v130, v2
	v_mul_f32_e32 v2, v130, v3
	v_cvt_pk_bf16_f32 v1, v1, v2
	v_mul_f32_e32 v2, v130, v4
	v_mul_f32_e32 v3, v130, v5
	v_cvt_pk_bf16_f32 v2, v2, v3
	v_mul_f32_e32 v3, v130, v6
	v_mul_f32_e32 v4, v130, v7
	v_cvt_pk_bf16_f32 v3, v3, v4
	v_mul_f32_e32 v4, v130, v15
	s_nop 1
	s_nop 0
	v_permlane32_swap_b32_e32 v0, v2
	v_permlane32_swap_b32_e32 v1, v3
	global_store_dwordx4 v[132:133], v[0:3], off offset:192
	s_nop 1
	v_mul_f32_e32 v0, v130, v8
	v_mul_f32_e32 v1, v130, v9
	v_cvt_pk_bf16_f32 v0, v0, v1
	v_mul_f32_e32 v1, v130, v10
	v_mul_f32_e32 v2, v130, v11
	v_cvt_pk_bf16_f32 v1, v1, v2
	v_mul_f32_e32 v2, v130, v12
	v_mul_f32_e32 v3, v130, v13
	v_cvt_pk_bf16_f32 v2, v2, v3
	v_mul_f32_e32 v3, v130, v14
	v_cvt_pk_bf16_f32 v3, v3, v4
	s_nop 0
	s_nop 1
	s_nop 0
	v_permlane32_swap_b32_e32 v0, v2
	v_permlane32_swap_b32_e32 v1, v3
	global_store_dwordx4 v[132:133], v[0:3], off offset:224
	s_cbranch_vccnz .LBB0_498
	s_barrier
	s_branch .LBB0_488
